# P3 static item remap: every 3-item workgroup gets (q8, q8, V), 2-item workgroups (K, q8|K|V); longest chain q8+q8+V instead of q8+K+V
# speedup vs baseline: 1.0188x; 1.0062x over previous
.LBB0_98:
	v_readlane_b32 s0, v254, 3
	v_readlane_b32 s4, v255, 61
	s_nop 3
	s_add_i32 s4, s4, s0
	v_readlane_b32 s0, v254, 4
	v_readlane_b32 s6, v254, 39
	v_readlane_b32 s1, v254, 5
	v_readlane_b32 s7, v254, 40
	s_xor_b64 s[6:7], s[6:7], s[0:1]
	v_writelane_b32 v254, s6, 39
	s_cmpk_gt_i32 s4, 0x28f
	s_nop 0
	v_writelane_b32 v254, s7, 40
	s_cbranch_scc1 .LBB0_234
.LBB0_99:
	v_writelane_b32 v255, s4, 61
	s_mov_b32 s0, 0
	s_cmp_ge_u32 s4, 0x90
	s_cselect_b32 s0, 0xb0, s0
	s_cmp_ge_u32 s4, 0x100
	s_cselect_b32 s0, 0xffffff90, s0
	s_cmp_ge_u32 s4, 0x1b0
	s_cselect_b32 s0, 0, s0
	s_cmp_ge_u32 s4, 0x1e8
	s_cselect_b32 s0, 0x90, s0
	s_cmp_ge_u32 s4, 0x200
	s_cselect_b32 s0, 0xffffffe8, s0
	s_add_i32 s4, s4, s0
	s_mov_b32 s94, s4
	s_cmpk_gt_i32 s4, 0x13f
	s_mov_b64 s[0:1], -1
	s_cbranch_scc0 .LBB0_197
	s_cmpk_gt_u32 s94, 0x1e7
	s_cbranch_scc0 .LBB0_131
	s_add_i32 s6, s94, 0xfffffe18
	s_mov_b32 s0, s35
	s_mov_b32 s1, s98
	s_mov_b32 s4, -1
	v_mbcnt_lo_u32_b32 v0, -1, 0
	s_cmpk_lt_u32 s6, 0xa0
	s_cselect_b64 s[20:21], -1, 0
	v_mbcnt_hi_u32_b32 v0, s4, v0
	v_lshl_add_u32 v136, s1, 6, v0
	s_lshl_b32 s7, s6, 8
	s_mov_b64 s[4:5], -1
	s_and_b64 vcc, exec, s[20:21]
	s_cbranch_vccz .LBB0_104
	s_mov_b64 s[38:39], 0x100
	s_mov_b64 s[4:5], 0
	s_cmp_lt_u32 s6, 32
	s_mov_b32 s48, s6
	s_mov_b64 s[50:51], 0
	s_mov_b64 s[52:53], 0
	s_cbranch_scc1 .LBB0_104
	s_add_i32 s1, s7, 0xffffe000
	s_and_b32 s34, s7, 0xf00
	s_ashr_i32 s48, s1, 12
	s_mov_b64 s[52:53], 0x800000
	s_mov_b64 s[38:39], 0x1100
	s_mov_b64 s[50:51], s[34:35]
	s_mov_b32 s34, 0x18000
	v_readlane_b32 s33, v254, 35
